# GU and WIN K-loops: peeled first trip whose first MFMA per accumulator takes C=0; the 128-register accumulator reset in the unit header is gone
# speedup vs baseline: 1.0014x; 1.0014x over previous
; #define LAS __attribute__((address_space(3)))
; template <class Epi, class Sched, bool ALIGN_EPI = false, bool SP2 = false>
; __device__ __forceinline__ void gemm_phase(PG8_LAS unsigned char* lds, const Gemm g, const Sched& S, const Epi& E) {
;     ...
;         const bool has_next = S.next(ui + 1, nxt);
;         const char* nA = has_next ? (const char*)g.A + (size_t)nxt.pm * tstep : cA; const char* nB = has_next ? (const char*)g.Bt + (size_t)nxt.pn * tstep : cB;
;         for (int t = 0; t < nt; t += 2) {
;             const bool last = (t == nt - 2);
;             const char* a1 = cA + (size_t)(t + 1) * kstep;
;             const char* a2 = last ? nA : cA + (size_t)(t + 2) * kstep; const char* b2 = last ? nB : cB + (size_t)(t + 2) * kstep;
;             const char* a3 = a2 + kstep; const char* b3 = b2 + kstep;
;             if (last && has_next) S.a_ready(nxt);
;             if (last) E.pre(cur, wid, lane);
;     __device__ __forceinline__ void pre(const pg8::Unit& u, int wid, int lane) const {
; #pragma unroll
;         for (int i = 0; i < 2; ++i) __builtin_amdgcn_global_load_lds((const unsigned*)(ssq + (size_t)(u.pm * 256 + wid * 32 + i * 16 + (lane >> 2)) * 16 + (lane & 3) * 4), (LAS unsigned*)(sl + (wid * 32 + i * 16) * 64), 16, 0, 0);
;     }
.LBB0_243:
	s_ashr_i32 s49, s48, 31
	s_lshl_b64 s[6:7], s[48:49], 19
	s_add_u32 s50, s10, s6
	s_addc_u32 s51, s11, s7
	s_and_b64 s[6:7], s[36:37], exec
	s_cselect_b32 s38, s51, s5
	s_cselect_b32 s39, s50, s4
	s_ashr_i32 s47, s46, 31
	s_lshl_b64 s[6:7], s[46:47], 19
	s_add_u32 s52, s12, s6
	v_readlane_b32 s6, v255, 3
	s_addc_u32 s53, s6, s7
	s_and_b64 s[6:7], s[36:37], exec
	s_cselect_b32 s49, s53, s1
	s_cselect_b32 s55, s52, s0
	s_lshl_b32 s47, s56, 8
	v_add_u32_e32 v0, s47, v198
	v_ashrrev_i32_e32 v1, 31, v0
	v_lshlrev_b64 v[2:3], 6, v[0:1]
	v_or_b32_e32 v0, 16, v0
	v_ashrrev_i32_e32 v1, 31, v0
	s_add_u32 s4, s4, 0x40080
	v_lshlrev_b64 v[0:1], 6, v[0:1]
	s_addc_u32 s5, s5, 0
	v_lshl_add_u64 v[128:129], v[160:161], 0, v[0:1]
	s_add_u32 s56, s0, 0x100
	v_lshl_add_u64 v[130:131], v[160:161], 0, v[2:3]
	s_addc_u32 s57, s1, 0
	s_mov_b32 s58, -2
	s_branch .Lwin_peel

; #define PG8_STAGE(bufoff, gbase, voff) do { _Pragma("unroll") for (int _i = 0; _i < 2; ++_i) \
;         __builtin_amdgcn_global_load_lds((const unsigned*)((const char*)(gbase) + (voff)[_i]), (PG8_LAS unsigned*)(lds + (bufoff) + ldsw + _i * 8192), 16, 0, 0); } while (0)
; #define PG8_LDA(dst, b, h) do { _Pragma("unroll") for (int m = 0; m < 4; ++m) _Pragma("unroll") for (int k = 0; k < 2; ++k) dst[m][k] = *(const PG8_LAS bf16x8*)(lds + PG8_SA(b, h) + aoff + m * 2048 + k * 1024); } while (0)
; #define PG8_LDB(dst, b, h) do { _Pragma("unroll") for (int n = 0; n < 2; ++n) _Pragma("unroll") for (int k = 0; k < 2; ++k) dst[n][k] = *(const PG8_LAS bf16x8*)(lds + PG8_SB(b, h) + boff + n * 2048 + k * 1024); } while (0)
; #define PG8_MMA(ai, bj, At, Bt) do { __builtin_amdgcn_s_setprio(1); _Pragma("unroll") for (int m = 0; m < 4; ++m) _Pragma("unroll") for (int n = 0; n < 2; ++n) _Pragma("unroll") for (int k = 0; k < 2; ++k) \
;         acc[ai][bj][m][n] = __builtin_amdgcn_mfma_f32_16x16x32_bf16(Bt[n][k], At[m][k], acc[ai][bj][m][n], 0, 0, 0); __builtin_amdgcn_s_setprio(0); } while (0)
; #define PG8_WAIT_V(n) asm volatile("s_waitcnt vmcnt(" #n ")" ::: "memory")
; #define PG8_WAIT_L(n) asm volatile("s_waitcnt lgkmcnt(" #n ")" ::: "memory")
; #define PG8_BAR __builtin_amdgcn_s_barrier()
; #define PG8_SCHED __builtin_amdgcn_sched_barrier(0)
; template <class Epi, class Sched, bool ALIGN_EPI = false, bool SP2 = false>
; __device__ __forceinline__ void gemm_phase(PG8_LAS unsigned char* lds, const Gemm g, const Sched& S, const Epi& E) {
;     ...
;             PG8_LDB(B0, 0, 0); PG8_LDB(B1, 0, 1); PG8_SCHED; PG8_LDA(At, 0, 0); PG8_STAGE(PG8_SA(1, 1), a1 + hstep, voffA);
;             PG8_WAIT_V(8); PG8_WAIT_L(0); PG8_BAR; PG8_MMA(0, 0, At, B0); PG8_MMA(0, 1, At, B1); PG8_BAR; PG8_SCHED;
;             PG8_LDA(At, 0, 1); PG8_STAGE(PG8_SB(0, 0), b2, voffB); PG8_STAGE(PG8_SB(0, 1), b2 + hstep, voffB); PG8_STAGE(PG8_SA(0, 0), a2, voffA);
;             PG8_WAIT_V(8); PG8_WAIT_L(0); PG8_BAR; PG8_MMA(1, 0, At, B0); PG8_MMA(1, 1, At, B1); PG8_BAR; PG8_SCHED;
.Lwin_peel:
	s_mov_b64 s[0:1], 0
	s_add_u32 s6, s4, 0xfffc0080
	s_addc_u32 s7, s5, -1
	s_and_b64 s[0:1], s[0:1], exec
	s_cselect_b32 s7, s38, s7
	s_cselect_b32 s6, s39, s6
	s_cselect_b32 s1, s49, s57
	s_cselect_b32 s0, s55, s56
	s_add_i32 s59, 0, 0x10000
	v_add_u32_e32 v144, s59, v197
	s_add_i32 s62, 0, 0x14000
	ds_read_b128 v[132:135], v144
	ds_read_b128 v[136:139], v144 offset:1024
	ds_read_b128 v[140:143], v144 offset:2048
	ds_read_b128 v[202:205], v144 offset:3072
	v_add_u32_e32 v144, s62, v197
	ds_read_b128 v[206:209], v144
	ds_read_b128 v[210:213], v144 offset:1024
	ds_read_b128 v[214:217], v144 offset:2048
	ds_read_b128 v[218:221], v144 offset:3072
	v_lshl_add_u64 v[172:173], s[4:5], 0, v[166:167]
	s_add_i32 m0, s25, 0xc000
	ds_read_b128 v[222:225], v199
	ds_read_b128 v[226:229], v199 offset:1024
	ds_read_b128 v[230:233], v199 offset:2048
	ds_read_b128 v[234:237], v199 offset:3072
	ds_read_b128 v[238:241], v199 offset:4096
	ds_read_b128 v[242:245], v199 offset:5120
	ds_read_b128 v[246:249], v199 offset:6144
	ds_read_b128 v[180:183], v199 offset:7168
	global_load_lds_dwordx4 v[172:173], off
	v_lshl_add_u64 v[172:173], s[4:5], 0, v[168:169]
	s_add_i32 m0, s25, 0xe000
	s_nop 0
	global_load_lds_dwordx4 v[172:173], off
	s_waitcnt vmcnt(8)
	s_waitcnt lgkmcnt(0)
	.p2alignl 3, 3212836864
	s_setprio 1
	s_barrier
	v_mfma_f32_16x16x32_bf16 v[124:127], v[132:135], v[222:225], 0
	v_mfma_f32_16x16x32_bf16 v[120:123], v[140:143], v[222:225], 0
	v_mfma_f32_16x16x32_bf16 v[108:111], v[132:135], v[230:233], 0
	v_mfma_f32_16x16x32_bf16 v[104:107], v[140:143], v[230:233], 0
	v_mfma_f32_16x16x32_bf16 v[92:95], v[132:135], v[238:241], 0
	v_mfma_f32_16x16x32_bf16 v[88:91], v[140:143], v[238:241], 0
	v_mfma_f32_16x16x32_bf16 v[76:79], v[132:135], v[246:249], 0
	v_mfma_f32_16x16x32_bf16 v[72:75], v[140:143], v[246:249], 0
	v_mfma_f32_16x16x32_bf16 v[124:127], v[136:139], v[226:229], v[124:127]
	v_mfma_f32_16x16x32_bf16 v[120:123], v[202:205], v[226:229], v[120:123]
	v_mfma_f32_16x16x32_bf16 v[108:111], v[136:139], v[234:237], v[108:111]
	v_mfma_f32_16x16x32_bf16 v[104:107], v[202:205], v[234:237], v[104:107]
	v_mfma_f32_16x16x32_bf16 v[92:95], v[136:139], v[242:245], v[92:95]
	v_mfma_f32_16x16x32_bf16 v[88:91], v[202:205], v[242:245], v[88:91]
	v_mfma_f32_16x16x32_bf16 v[76:79], v[136:139], v[180:183], v[76:79]
	v_mfma_f32_16x16x32_bf16 v[72:75], v[202:205], v[180:183], v[72:75]
	s_setprio 0
	s_setprio 1
	v_mfma_f32_16x16x32_bf16 v[116:119], v[206:209], v[222:225], 0
	v_mfma_f32_16x16x32_bf16 v[112:115], v[214:217], v[222:225], 0
	v_mfma_f32_16x16x32_bf16 v[100:103], v[206:209], v[230:233], 0
	v_mfma_f32_16x16x32_bf16 v[96:99], v[214:217], v[230:233], 0
	v_mfma_f32_16x16x32_bf16 v[84:87], v[206:209], v[238:241], 0
	v_mfma_f32_16x16x32_bf16 v[80:83], v[214:217], v[238:241], 0
	v_mfma_f32_16x16x32_bf16 v[68:71], v[206:209], v[246:249], 0
	v_mfma_f32_16x16x32_bf16 v[64:67], v[214:217], v[246:249], 0
	v_mfma_f32_16x16x32_bf16 v[116:119], v[210:213], v[226:229], v[116:119]
	v_mfma_f32_16x16x32_bf16 v[112:115], v[218:221], v[226:229], v[112:115]
	v_mfma_f32_16x16x32_bf16 v[100:103], v[210:213], v[234:237], v[100:103]
	v_mfma_f32_16x16x32_bf16 v[96:99], v[218:221], v[234:237], v[96:99]
	v_mfma_f32_16x16x32_bf16 v[84:87], v[210:213], v[242:245], v[84:87]
	v_mfma_f32_16x16x32_bf16 v[80:83], v[218:221], v[242:245], v[80:83]
	v_mfma_f32_16x16x32_bf16 v[68:71], v[210:213], v[180:183], v[68:71]
	v_mfma_f32_16x16x32_bf16 v[64:67], v[218:221], v[180:183], v[64:67]
	s_barrier
	s_setprio 0
	s_add_i32 s59, s59, s24
	v_lshl_add_u64 v[172:173], s[0:1], 0, v[154:155]
	s_mov_b32 m0, s59
	ds_read_b128 v[180:183], v199 offset:16384
	ds_read_b128 v[222:225], v199 offset:17408
	ds_read_b128 v[226:229], v199 offset:18432
	ds_read_b128 v[230:233], v199 offset:19456
	ds_read_b128 v[234:237], v199 offset:20480
	ds_read_b128 v[238:241], v199 offset:21504
	ds_read_b128 v[242:245], v199 offset:22528
	ds_read_b128 v[246:249], v199 offset:23552
	global_load_lds_dwordx4 v[172:173], off
	s_add_i32 m0, s59, 0x2000
	s_add_u32 s60, s0, 0x40000
	v_lshl_add_u64 v[184:185], s[0:1], 0, v[150:151]
	s_addc_u32 s61, s1, 0
	s_add_i32 s59, s62, s24
	global_load_lds_dwordx4 v[184:185], off
	v_lshl_add_u64 v[186:187], s[60:61], 0, v[154:155]
	s_mov_b32 m0, s59
	v_lshl_add_u64 v[188:189], s[6:7], 0, v[152:153]
	global_load_lds_dwordx4 v[186:187], off
	v_lshl_add_u64 v[186:187], s[60:61], 0, v[150:151]
	s_add_i32 m0, s59, 0x2000
	s_nop 0
	global_load_lds_dwordx4 v[186:187], off
	v_lshl_add_u64 v[186:187], s[6:7], 0, v[156:157]
	s_mov_b32 m0, s25
	s_nop 0
	global_load_lds_dwordx4 v[186:187], off
	s_mov_b32 m0, s26
	s_nop 0
	global_load_lds_dwordx4 v[188:189], off
	s_waitcnt vmcnt(8)
	s_waitcnt lgkmcnt(0)
	.p2alignl 3, 3212836864
	s_setprio 1
	s_barrier
; #define PG8_STAGE(bufoff, gbase, voff) do { _Pragma("unroll") for (int _i = 0; _i < 2; ++_i) \
;         __builtin_amdgcn_global_load_lds((const unsigned*)((const char*)(gbase) + (voff)[_i]), (PG8_LAS unsigned*)(lds + (bufoff) + ldsw + _i * 8192), 16, 0, 0); } while (0)
; #define PG8_LDA(dst, b, h) do { _Pragma("unroll") for (int m = 0; m < 4; ++m) _Pragma("unroll") for (int k = 0; k < 2; ++k) dst[m][k] = *(const PG8_LAS bf16x8*)(lds + PG8_SA(b, h) + aoff + m * 2048 + k * 1024); } while (0)
; #define PG8_LDB(dst, b, h) do { _Pragma("unroll") for (int n = 0; n < 2; ++n) _Pragma("unroll") for (int k = 0; k < 2; ++k) dst[n][k] = *(const PG8_LAS bf16x8*)(lds + PG8_SB(b, h) + boff + n * 2048 + k * 1024); } while (0)
; #define PG8_MMA(ai, bj, At, Bt) do { __builtin_amdgcn_s_setprio(1); _Pragma("unroll") for (int m = 0; m < 4; ++m) _Pragma("unroll") for (int n = 0; n < 2; ++n) _Pragma("unroll") for (int k = 0; k < 2; ++k) \
;         acc[ai][bj][m][n] = __builtin_amdgcn_mfma_f32_16x16x32_bf16(Bt[n][k], At[m][k], acc[ai][bj][m][n], 0, 0, 0); __builtin_amdgcn_s_setprio(0); } while (0)
; #define PG8_WAIT_V(n) asm volatile("s_waitcnt vmcnt(" #n ")" ::: "memory")
; #define PG8_WAIT_L(n) asm volatile("s_waitcnt lgkmcnt(" #n ")" ::: "memory")
; #define PG8_BAR __builtin_amdgcn_s_barrier()
; #define PG8_SCHED __builtin_amdgcn_sched_barrier(0)
; template <class Epi, class Sched, bool ALIGN_EPI = false, bool SP2 = false>
; __device__ __forceinline__ void gemm_phase(PG8_LAS unsigned char* lds, const Gemm g, const Sched& S, const Epi& E) {
;     ...
;             PG8_WAIT_V(8); PG8_WAIT_L(0); PG8_BAR; PG8_MMA(0, 0, At, B0); PG8_MMA(0, 1, At, B1); PG8_BAR; PG8_SCHED;
;             PG8_LDA(At, 0, 1); PG8_STAGE(PG8_SB(0, 0), b2, voffB); PG8_STAGE(PG8_SB(0, 1), b2 + hstep, voffB); PG8_STAGE(PG8_SA(0, 0), a2, voffA);
;             PG8_WAIT_V(8); PG8_WAIT_L(0); PG8_BAR; PG8_MMA(1, 0, At, B0); PG8_MMA(1, 1, At, B1); PG8_BAR; PG8_SCHED;
;             PG8_LDB(B0, 1, 0); PG8_LDB(B1, 1, 1); PG8_SCHED; PG8_LDA(At, 1, 0); PG8_STAGE(PG8_SA(0, 1), a2 + hstep, voffA);
;             PG8_WAIT_V(8); PG8_WAIT_L(0); PG8_BAR; PG8_MMA(0, 0, At, B0); PG8_MMA(0, 1, At, B1); PG8_BAR; PG8_SCHED;
	v_mfma_f32_16x16x32_bf16 v[60:63], v[132:135], v[180:183], 0
	v_mfma_f32_16x16x32_bf16 v[56:59], v[140:143], v[180:183], 0
	v_mfma_f32_16x16x32_bf16 v[44:47], v[132:135], v[226:229], 0
	v_mfma_f32_16x16x32_bf16 v[40:43], v[140:143], v[226:229], 0
	v_mfma_f32_16x16x32_bf16 v[28:31], v[132:135], v[234:237], 0
	v_mfma_f32_16x16x32_bf16 v[24:27], v[140:143], v[234:237], 0
	v_mfma_f32_16x16x32_bf16 v[12:15], v[132:135], v[242:245], 0
	v_mfma_f32_16x16x32_bf16 v[8:11], v[140:143], v[242:245], 0
	v_mfma_f32_16x16x32_bf16 v[60:63], v[136:139], v[222:225], v[60:63]
	v_mfma_f32_16x16x32_bf16 v[56:59], v[202:205], v[222:225], v[56:59]
	v_mfma_f32_16x16x32_bf16 v[44:47], v[136:139], v[230:233], v[44:47]
	v_mfma_f32_16x16x32_bf16 v[40:43], v[202:205], v[230:233], v[40:43]
	v_mfma_f32_16x16x32_bf16 v[28:31], v[136:139], v[238:241], v[28:31]
	v_mfma_f32_16x16x32_bf16 v[24:27], v[202:205], v[238:241], v[24:27]
	v_mfma_f32_16x16x32_bf16 v[12:15], v[136:139], v[246:249], v[12:15]
	v_mfma_f32_16x16x32_bf16 v[8:11], v[202:205], v[246:249], v[8:11]
	s_setprio 0
	s_setprio 1
	v_mfma_f32_16x16x32_bf16 v[52:55], v[206:209], v[180:183], 0
	v_mfma_f32_16x16x32_bf16 v[48:51], v[214:217], v[180:183], 0
	v_mfma_f32_16x16x32_bf16 v[36:39], v[206:209], v[226:229], 0
	v_mfma_f32_16x16x32_bf16 v[32:35], v[214:217], v[226:229], 0
	v_mfma_f32_16x16x32_bf16 v[20:23], v[206:209], v[234:237], 0
	v_mfma_f32_16x16x32_bf16 v[16:19], v[214:217], v[234:237], 0
	v_mfma_f32_16x16x32_bf16 v[4:7], v[206:209], v[242:245], 0
	v_mfma_f32_16x16x32_bf16 v[0:3], v[214:217], v[242:245], 0
	v_mfma_f32_16x16x32_bf16 v[52:55], v[210:213], v[222:225], v[52:55]
	v_mfma_f32_16x16x32_bf16 v[48:51], v[218:221], v[222:225], v[48:51]
	v_mfma_f32_16x16x32_bf16 v[36:39], v[210:213], v[230:233], v[36:39]
	v_mfma_f32_16x16x32_bf16 v[32:35], v[218:221], v[230:233], v[32:35]
	v_mfma_f32_16x16x32_bf16 v[20:23], v[210:213], v[238:241], v[20:23]
	v_mfma_f32_16x16x32_bf16 v[16:19], v[218:221], v[238:241], v[16:19]
	v_mfma_f32_16x16x32_bf16 v[4:7], v[210:213], v[246:249], v[4:7]
	v_mfma_f32_16x16x32_bf16 v[0:3], v[218:221], v[246:249], v[0:3]
	s_barrier
	s_setprio 0
	s_add_i32 s59, 0, 0x18000
	v_add_u32_e32 v144, s59, v197
	s_add_i32 s60, 0, 0x1c000
	ds_read_b128 v[132:135], v144
	ds_read_b128 v[136:139], v144 offset:1024
	ds_read_b128 v[140:143], v144 offset:2048
	ds_read_b128 v[180:183], v144 offset:3072
	v_add_u32_e32 v144, s60, v197
	ds_read_b128 v[202:205], v144
	ds_read_b128 v[206:209], v144 offset:1024
	ds_read_b128 v[210:213], v144 offset:2048
	ds_read_b128 v[214:217], v144 offset:3072
	s_add_u32 s6, s6, 0x40000
	s_addc_u32 s7, s7, 0
	s_mov_b32 m0, s27
	v_lshl_add_u64 v[190:191], s[6:7], 0, v[156:157]
	ds_read_b128 v[218:221], v199 offset:32768
	ds_read_b128 v[222:225], v199 offset:33792
	ds_read_b128 v[226:229], v199 offset:34816
	ds_read_b128 v[230:233], v199 offset:35840
	ds_read_b128 v[234:237], v199 offset:36864
	ds_read_b128 v[238:241], v199 offset:37888
	ds_read_b128 v[242:245], v199 offset:38912
	ds_read_b128 v[246:249], v199 offset:39936
	global_load_lds_dwordx4 v[190:191], off
	v_lshl_add_u64 v[190:191], s[6:7], 0, v[152:153]
	s_mov_b32 m0, s28
	s_nop 0
	global_load_lds_dwordx4 v[190:191], off
	s_waitcnt vmcnt(8)
	s_waitcnt lgkmcnt(0)
	.p2alignl 3, 3212836864
	s_setprio 1
	s_barrier
	v_mfma_f32_16x16x32_bf16 v[124:127], v[132:135], v[218:221], v[124:127]
	v_mfma_f32_16x16x32_bf16 v[120:123], v[140:143], v[218:221], v[120:123]
	v_mfma_f32_16x16x32_bf16 v[108:111], v[132:135], v[226:229], v[108:111]
	v_mfma_f32_16x16x32_bf16 v[104:107], v[140:143], v[226:229], v[104:107]
	v_mfma_f32_16x16x32_bf16 v[92:95], v[132:135], v[234:237], v[92:95]
	v_mfma_f32_16x16x32_bf16 v[88:91], v[140:143], v[234:237], v[88:91]
	v_mfma_f32_16x16x32_bf16 v[76:79], v[132:135], v[242:245], v[76:79]
	v_mfma_f32_16x16x32_bf16 v[72:75], v[140:143], v[242:245], v[72:75]
	v_mfma_f32_16x16x32_bf16 v[124:127], v[136:139], v[222:225], v[124:127]
	v_mfma_f32_16x16x32_bf16 v[120:123], v[180:183], v[222:225], v[120:123]
	v_mfma_f32_16x16x32_bf16 v[108:111], v[136:139], v[230:233], v[108:111]
	v_mfma_f32_16x16x32_bf16 v[104:107], v[180:183], v[230:233], v[104:107]
	v_mfma_f32_16x16x32_bf16 v[92:95], v[136:139], v[238:241], v[92:95]
	v_mfma_f32_16x16x32_bf16 v[88:91], v[180:183], v[238:241], v[88:91]
	v_mfma_f32_16x16x32_bf16 v[76:79], v[136:139], v[246:249], v[76:79]
	v_mfma_f32_16x16x32_bf16 v[72:75], v[180:183], v[246:249], v[72:75]
	s_setprio 0
	s_setprio 1
	v_mfma_f32_16x16x32_bf16 v[116:119], v[202:205], v[218:221], v[116:119]
	v_mfma_f32_16x16x32_bf16 v[112:115], v[210:213], v[218:221], v[112:115]
	v_mfma_f32_16x16x32_bf16 v[100:103], v[202:205], v[226:229], v[100:103]
	v_mfma_f32_16x16x32_bf16 v[96:99], v[210:213], v[226:229], v[96:99]
	v_mfma_f32_16x16x32_bf16 v[84:87], v[202:205], v[234:237], v[84:87]
	v_mfma_f32_16x16x32_bf16 v[80:83], v[210:213], v[234:237], v[80:83]
	v_mfma_f32_16x16x32_bf16 v[68:71], v[202:205], v[242:245], v[68:71]
	v_mfma_f32_16x16x32_bf16 v[64:67], v[210:213], v[242:245], v[64:67]
	v_mfma_f32_16x16x32_bf16 v[116:119], v[206:209], v[222:225], v[116:119]
	v_mfma_f32_16x16x32_bf16 v[112:115], v[214:217], v[222:225], v[112:115]
	v_mfma_f32_16x16x32_bf16 v[100:103], v[206:209], v[230:233], v[100:103]
	v_mfma_f32_16x16x32_bf16 v[96:99], v[214:217], v[230:233], v[96:99]
	v_mfma_f32_16x16x32_bf16 v[84:87], v[206:209], v[238:241], v[84:87]
	v_mfma_f32_16x16x32_bf16 v[80:83], v[214:217], v[238:241], v[80:83]
	v_mfma_f32_16x16x32_bf16 v[68:71], v[206:209], v[246:249], v[68:71]
	v_mfma_f32_16x16x32_bf16 v[64:67], v[214:217], v[246:249], v[64:67]
	s_barrier
; #define PG8_STAGE(bufoff, gbase, voff) do { _Pragma("unroll") for (int _i = 0; _i < 2; ++_i) \
;         __builtin_amdgcn_global_load_lds((const unsigned*)((const char*)(gbase) + (voff)[_i]), (PG8_LAS unsigned*)(lds + (bufoff) + ldsw + _i * 8192), 16, 0, 0); } while (0)
; #define PG8_LDA(dst, b, h) do { _Pragma("unroll") for (int m = 0; m < 4; ++m) _Pragma("unroll") for (int k = 0; k < 2; ++k) dst[m][k] = *(const PG8_LAS bf16x8*)(lds + PG8_SA(b, h) + aoff + m * 2048 + k * 1024); } while (0)
; #define PG8_MMA(ai, bj, At, Bt) do { __builtin_amdgcn_s_setprio(1); _Pragma("unroll") for (int m = 0; m < 4; ++m) _Pragma("unroll") for (int n = 0; n < 2; ++n) _Pragma("unroll") for (int k = 0; k < 2; ++k) \
;         acc[ai][bj][m][n] = __builtin_amdgcn_mfma_f32_16x16x32_bf16(Bt[n][k], At[m][k], acc[ai][bj][m][n], 0, 0, 0); __builtin_amdgcn_s_setprio(0); } while (0)
; #define PG8_WAIT_V(n) asm volatile("s_waitcnt vmcnt(" #n ")" ::: "memory")
; #define PG8_WAIT_L(n) asm volatile("s_waitcnt lgkmcnt(" #n ")" ::: "memory")
; #define PG8_BAR __builtin_amdgcn_s_barrier()
; #define PG8_SCHED __builtin_amdgcn_sched_barrier(0)
; template <class Epi, class Sched, bool ALIGN_EPI = false, bool SP2 = false>
; __device__ __forceinline__ void gemm_phase(PG8_LAS unsigned char* lds, const Gemm g, const Sched& S, const Epi& E) {
;     ...
;             PG8_WAIT_V(8); PG8_WAIT_L(0); PG8_BAR; PG8_MMA(0, 0, At, B0); PG8_MMA(0, 1, At, B1); PG8_BAR; PG8_SCHED;
;             PG8_LDA(At, 1, 1); PG8_STAGE(PG8_SB(1, 0), b3, voffB); PG8_STAGE(PG8_SB(1, 1), b3 + hstep, voffB); PG8_STAGE(PG8_SA(1, 0), a3, voffA);
;             PG8_WAIT_V(8); PG8_WAIT_L(0); PG8_BAR; PG8_MMA(1, 0, At, B0); PG8_MMA(1, 1, At, B1); PG8_BAR; PG8_SCHED;
	s_setprio 0
	s_add_i32 s6, s59, s24
	v_lshl_add_u64 v[172:173], v[172:173], 0, s[94:95]
	s_mov_b32 m0, s6
	ds_read_b128 v[218:221], v199 offset:49152
	ds_read_b128 v[222:225], v199 offset:50176
	ds_read_b128 v[226:229], v199 offset:51200
	ds_read_b128 v[230:233], v199 offset:52224
	ds_read_b128 v[234:237], v199 offset:53248
	ds_read_b128 v[238:241], v199 offset:54272
	ds_read_b128 v[242:245], v199 offset:55296
	ds_read_b128 v[246:249], v199 offset:56320
	global_load_lds_dwordx4 v[172:173], off
	s_add_i32 m0, s6, 0x2000
	s_add_u32 s0, s0, 0x40080
	v_lshl_add_u64 v[172:173], v[184:185], 0, s[94:95]
	s_addc_u32 s1, s1, 0
	s_add_i32 s6, s60, s24
	global_load_lds_dwordx4 v[172:173], off
	v_lshl_add_u64 v[172:173], s[0:1], 0, v[154:155]
	s_mov_b32 m0, s6
	s_nop 0
	global_load_lds_dwordx4 v[172:173], off
	v_lshl_add_u64 v[172:173], s[0:1], 0, v[150:151]
	s_add_i32 m0, s6, 0x2000
	s_nop 0
	global_load_lds_dwordx4 v[172:173], off
	v_lshl_add_u64 v[172:173], v[186:187], 0, s[94:95]
	s_mov_b32 m0, s29
	s_nop 0
	global_load_lds_dwordx4 v[172:173], off
	v_lshl_add_u64 v[172:173], v[188:189], 0, s[94:95]
	s_mov_b32 m0, s30
	s_nop 0
	global_load_lds_dwordx4 v[172:173], off
	s_waitcnt vmcnt(8)
	s_waitcnt lgkmcnt(0)
	.p2alignl 3, 3212836864
	s_setprio 1
	s_barrier
	v_mfma_f32_16x16x32_bf16 v[60:63], v[132:135], v[218:221], v[60:63]
	v_mfma_f32_16x16x32_bf16 v[56:59], v[140:143], v[218:221], v[56:59]
	v_mfma_f32_16x16x32_bf16 v[44:47], v[132:135], v[226:229], v[44:47]
	v_mfma_f32_16x16x32_bf16 v[40:43], v[140:143], v[226:229], v[40:43]
	v_mfma_f32_16x16x32_bf16 v[28:31], v[132:135], v[234:237], v[28:31]
	v_mfma_f32_16x16x32_bf16 v[24:27], v[140:143], v[234:237], v[24:27]
	v_mfma_f32_16x16x32_bf16 v[12:15], v[132:135], v[242:245], v[12:15]
	v_mfma_f32_16x16x32_bf16 v[8:11], v[140:143], v[242:245], v[8:11]
	v_mfma_f32_16x16x32_bf16 v[60:63], v[136:139], v[222:225], v[60:63]
	v_mfma_f32_16x16x32_bf16 v[56:59], v[180:183], v[222:225], v[56:59]
	v_mfma_f32_16x16x32_bf16 v[44:47], v[136:139], v[230:233], v[44:47]
	v_mfma_f32_16x16x32_bf16 v[40:43], v[180:183], v[230:233], v[40:43]
	v_mfma_f32_16x16x32_bf16 v[28:31], v[136:139], v[238:241], v[28:31]
	v_mfma_f32_16x16x32_bf16 v[24:27], v[180:183], v[238:241], v[24:27]
	v_mfma_f32_16x16x32_bf16 v[12:15], v[136:139], v[246:249], v[12:15]
	v_mfma_f32_16x16x32_bf16 v[8:11], v[180:183], v[246:249], v[8:11]
	s_setprio 0
	s_setprio 1
	v_mfma_f32_16x16x32_bf16 v[52:55], v[202:205], v[218:221], v[52:55]
	v_mfma_f32_16x16x32_bf16 v[48:51], v[210:213], v[218:221], v[48:51]
	v_mfma_f32_16x16x32_bf16 v[36:39], v[202:205], v[226:229], v[36:39]
	v_mfma_f32_16x16x32_bf16 v[32:35], v[210:213], v[226:229], v[32:35]
	v_mfma_f32_16x16x32_bf16 v[20:23], v[202:205], v[234:237], v[20:23]
	v_mfma_f32_16x16x32_bf16 v[16:19], v[210:213], v[234:237], v[16:19]
	v_mfma_f32_16x16x32_bf16 v[4:7], v[202:205], v[242:245], v[4:7]
	v_mfma_f32_16x16x32_bf16 v[0:3], v[210:213], v[242:245], v[0:3]
	v_mfma_f32_16x16x32_bf16 v[52:55], v[206:209], v[222:225], v[52:55]
	v_mfma_f32_16x16x32_bf16 v[48:51], v[214:217], v[222:225], v[48:51]
	v_mfma_f32_16x16x32_bf16 v[36:39], v[206:209], v[230:233], v[36:39]
	v_mfma_f32_16x16x32_bf16 v[32:35], v[214:217], v[230:233], v[32:35]
	v_mfma_f32_16x16x32_bf16 v[20:23], v[206:209], v[238:241], v[20:23]
	v_mfma_f32_16x16x32_bf16 v[16:19], v[214:217], v[238:241], v[16:19]
	v_mfma_f32_16x16x32_bf16 v[4:7], v[206:209], v[246:249], v[4:7]
	v_mfma_f32_16x16x32_bf16 v[0:3], v[214:217], v[246:249], v[0:3]
	s_barrier
	s_setprio 0
	s_add_i32 s58, s58, 2
	s_add_u32 s4, s4, 0x100
	s_addc_u32 s5, s5, 0
	s_add_u32 s56, s56, 0x100
	s_addc_u32 s57, s57, 0
	s_cmp_gt_u32 s58, 13
	s_branch .LBB0_245

; #define LAS __attribute__((address_space(3)))
; template <class Epi, class Sched, bool ALIGN_EPI = false, bool SP2 = false>
; __device__ __forceinline__ void gemm_phase(PG8_LAS unsigned char* lds, const Gemm g, const Sched& S, const Epi& E) {
;     ...
;         const bool has_next = S.next(ui + 1, nxt);
;         const char* nA = has_next ? (const char*)g.A + (size_t)nxt.pm * tstep : cA; const char* nB = has_next ? (const char*)g.Bt + (size_t)nxt.pn * tstep : cB;
;         for (int t = 0; t < nt; t += 2) {
;             const bool last = (t == nt - 2);
;             const char* a1 = cA + (size_t)(t + 1) * kstep;
;             const char* a2 = last ? nA : cA + (size_t)(t + 2) * kstep; const char* b2 = last ? nB : cB + (size_t)(t + 2) * kstep;
;             const char* a3 = a2 + kstep; const char* b3 = b2 + kstep;
;             if (last && has_next) S.a_ready(nxt);
;             if (last) E.pre(cur, wid, lane);
;     __device__ __forceinline__ void pre(const pg8::Unit& u, int wid, int lane) const {
; #pragma unroll
;         for (int i = 0; i < 2; ++i) __builtin_amdgcn_global_load_lds((const unsigned*)(ssq + (size_t)(u.pm * 256 + wid * 32 + i * 16 + (lane >> 2)) * 16 + (lane & 3) * 4), (LAS unsigned*)(sl + (wid * 32 + i * 16) * 64), 16, 0, 0);
;     }
.LBB0_1646:
	s_ashr_i32 s47, s46, 31
	s_lshl_b64 s[6:7], s[46:47], 19
	s_add_u32 s48, s10, s6
	s_addc_u32 s49, s11, s7
	s_and_b64 s[6:7], s[36:37], exec
	s_cselect_b32 s39, s49, s5
	s_cselect_b32 s47, s48, s4
	s_ashr_i32 s45, s44, 31
	s_lshl_b64 s[6:7], s[44:45], 19
	s_add_u32 s50, s24, s6
	s_addc_u32 s51, s25, s7
	s_and_b64 s[6:7], s[36:37], exec
	s_cselect_b32 s53, s51, s1
	s_cselect_b32 s54, s50, s0
	s_lshl_b32 s45, s55, 8
	v_add_u32_e32 v0, s45, v167
	v_ashrrev_i32_e32 v1, 31, v0
	v_lshlrev_b64 v[2:3], 6, v[0:1]
	v_or_b32_e32 v0, 16, v0
	v_ashrrev_i32_e32 v1, 31, v0
	s_add_u32 s4, s4, 0x40080
	v_lshlrev_b64 v[0:1], 6, v[0:1]
	s_addc_u32 s5, s5, 0
	v_lshl_add_u64 v[128:129], v[156:157], 0, v[0:1]
	s_add_u32 s55, s0, 0x100
	v_lshl_add_u64 v[130:131], v[156:157], 0, v[2:3]
	s_addc_u32 s56, s1, 0
	s_mov_b32 s57, -2
	s_branch .Lgu_peel

; #define PG8_STAGE(bufoff, gbase, voff) do { _Pragma("unroll") for (int _i = 0; _i < 2; ++_i) \
;         __builtin_amdgcn_global_load_lds((const unsigned*)((const char*)(gbase) + (voff)[_i]), (PG8_LAS unsigned*)(lds + (bufoff) + ldsw + _i * 8192), 16, 0, 0); } while (0)
; #define PG8_LDA(dst, b, h) do { _Pragma("unroll") for (int m = 0; m < 4; ++m) _Pragma("unroll") for (int k = 0; k < 2; ++k) dst[m][k] = *(const PG8_LAS bf16x8*)(lds + PG8_SA(b, h) + aoff + m * 2048 + k * 1024); } while (0)
; #define PG8_LDB(dst, b, h) do { _Pragma("unroll") for (int n = 0; n < 2; ++n) _Pragma("unroll") for (int k = 0; k < 2; ++k) dst[n][k] = *(const PG8_LAS bf16x8*)(lds + PG8_SB(b, h) + boff + n * 2048 + k * 1024); } while (0)
; #define PG8_MMA(ai, bj, At, Bt) do { __builtin_amdgcn_s_setprio(1); _Pragma("unroll") for (int m = 0; m < 4; ++m) _Pragma("unroll") for (int n = 0; n < 2; ++n) _Pragma("unroll") for (int k = 0; k < 2; ++k) \
;         acc[ai][bj][m][n] = __builtin_amdgcn_mfma_f32_16x16x32_bf16(Bt[n][k], At[m][k], acc[ai][bj][m][n], 0, 0, 0); __builtin_amdgcn_s_setprio(0); } while (0)
; #define PG8_WAIT_V(n) asm volatile("s_waitcnt vmcnt(" #n ")" ::: "memory")
; #define PG8_WAIT_L(n) asm volatile("s_waitcnt lgkmcnt(" #n ")" ::: "memory")
; #define PG8_BAR __builtin_amdgcn_s_barrier()
; #define PG8_SCHED __builtin_amdgcn_sched_barrier(0)
; template <class Epi, class Sched, bool ALIGN_EPI = false, bool SP2 = false>
; __device__ __forceinline__ void gemm_phase(PG8_LAS unsigned char* lds, const Gemm g, const Sched& S, const Epi& E) {
;     ...
;             PG8_LDB(B0, 0, 0); PG8_LDB(B1, 0, 1); PG8_SCHED; PG8_LDA(At, 0, 0); PG8_STAGE(PG8_SA(1, 1), a1 + hstep, voffA);
;             PG8_WAIT_V(8); PG8_WAIT_L(0); PG8_BAR; PG8_MMA(0, 0, At, B0); PG8_MMA(0, 1, At, B1); PG8_BAR; PG8_SCHED;
;             PG8_LDA(At, 0, 1); PG8_STAGE(PG8_SB(0, 0), b2, voffB); PG8_STAGE(PG8_SB(0, 1), b2 + hstep, voffB); PG8_STAGE(PG8_SA(0, 0), a2, voffA);
;             PG8_WAIT_V(8); PG8_WAIT_L(0); PG8_BAR; PG8_MMA(1, 0, At, B0); PG8_MMA(1, 1, At, B1); PG8_BAR; PG8_SCHED;
.Lgu_peel:
	s_mov_b64 s[0:1], 0
	s_add_u32 s6, s4, 0xfffc0080
	s_addc_u32 s7, s5, -1
	s_and_b64 s[0:1], s[0:1], exec
	s_cselect_b32 s7, s39, s7
	s_cselect_b32 s6, s47, s6
	s_cselect_b32 s1, s53, s56
	s_cselect_b32 s0, s54, s55
	s_cmp_eq_u32 s57, -2
	s_cselect_b32 vcc_lo, 1, 0
	s_cmp_gt_u32 s35, 1
	s_cselect_b32 vcc_lo, vcc_lo, 0
	s_add_i32 s58, 0, 0x10000
	v_add_u32_e32 v162, s58, v165
	s_add_i32 s60, 0, 0x14000
	ds_read_b128 v[132:135], v162
	ds_read_b128 v[136:139], v162 offset:1024
	ds_read_b128 v[140:143], v162 offset:2048
	ds_read_b128 v[180:183], v162 offset:3072
	v_add_u32_e32 v162, s60, v165
	ds_read_b128 v[200:203], v162
	ds_read_b128 v[204:207], v162 offset:1024
	ds_read_b128 v[208:211], v162 offset:2048
	ds_read_b128 v[212:215], v162 offset:3072
	v_lshl_add_u64 v[168:169], s[4:5], 0, v[158:159]
	s_add_i32 m0, s27, 0xc000
	ds_read_b128 v[216:219], v197
	ds_read_b128 v[220:223], v197 offset:1024
	ds_read_b128 v[224:227], v197 offset:2048
	ds_read_b128 v[228:231], v197 offset:3072
	ds_read_b128 v[232:235], v197 offset:4096
	ds_read_b128 v[236:239], v197 offset:5120
	ds_read_b128 v[240:243], v197 offset:6144
	ds_read_b128 v[244:247], v197 offset:7168
	global_load_lds_dwordx4 v[168:169], off
	v_lshl_add_u64 v[168:169], s[4:5], 0, v[160:161]
	s_add_i32 m0, s27, 0xe000
	s_nop 0
	global_load_lds_dwordx4 v[168:169], off
	s_waitcnt vmcnt(16)
	s_cmp_lg_u32 vcc_lo, 0
	s_cbranch_scc1 .Lgu_relaxed0_p
	s_waitcnt vmcnt(8)
.Lgu_relaxed0_p:
	s_waitcnt lgkmcnt(0)
	.p2alignl 3, 3212836864
	s_setprio 1
	s_barrier
	v_mfma_f32_16x16x32_bf16 v[124:127], v[132:135], v[216:219], 0
	v_mfma_f32_16x16x32_bf16 v[116:119], v[140:143], v[216:219], 0
	v_mfma_f32_16x16x32_bf16 v[108:111], v[132:135], v[224:227], 0
	v_mfma_f32_16x16x32_bf16 v[100:103], v[140:143], v[224:227], 0
	v_mfma_f32_16x16x32_bf16 v[92:95], v[132:135], v[232:235], 0
	v_mfma_f32_16x16x32_bf16 v[84:87], v[140:143], v[232:235], 0
	v_mfma_f32_16x16x32_bf16 v[76:79], v[132:135], v[240:243], 0
	v_mfma_f32_16x16x32_bf16 v[68:71], v[140:143], v[240:243], 0
	v_mfma_f32_16x16x32_bf16 v[124:127], v[136:139], v[220:223], v[124:127]
	v_mfma_f32_16x16x32_bf16 v[116:119], v[180:183], v[220:223], v[116:119]
	v_mfma_f32_16x16x32_bf16 v[108:111], v[136:139], v[228:231], v[108:111]
	v_mfma_f32_16x16x32_bf16 v[100:103], v[180:183], v[228:231], v[100:103]
	v_mfma_f32_16x16x32_bf16 v[92:95], v[136:139], v[236:239], v[92:95]
	v_mfma_f32_16x16x32_bf16 v[84:87], v[180:183], v[236:239], v[84:87]
	v_mfma_f32_16x16x32_bf16 v[76:79], v[136:139], v[244:247], v[76:79]
	v_mfma_f32_16x16x32_bf16 v[68:71], v[180:183], v[244:247], v[68:71]
	s_setprio 0
	s_setprio 1
	v_mfma_f32_16x16x32_bf16 v[120:123], v[200:203], v[216:219], 0
	v_mfma_f32_16x16x32_bf16 v[112:115], v[208:211], v[216:219], 0
	v_mfma_f32_16x16x32_bf16 v[104:107], v[200:203], v[224:227], 0
	v_mfma_f32_16x16x32_bf16 v[96:99], v[208:211], v[224:227], 0
	v_mfma_f32_16x16x32_bf16 v[88:91], v[200:203], v[232:235], 0
	v_mfma_f32_16x16x32_bf16 v[80:83], v[208:211], v[232:235], 0
	v_mfma_f32_16x16x32_bf16 v[72:75], v[200:203], v[240:243], 0
	v_mfma_f32_16x16x32_bf16 v[64:67], v[208:211], v[240:243], 0
	v_mfma_f32_16x16x32_bf16 v[120:123], v[204:207], v[220:223], v[120:123]
	v_mfma_f32_16x16x32_bf16 v[112:115], v[212:215], v[220:223], v[112:115]
	v_mfma_f32_16x16x32_bf16 v[104:107], v[204:207], v[228:231], v[104:107]
	v_mfma_f32_16x16x32_bf16 v[96:99], v[212:215], v[228:231], v[96:99]
	v_mfma_f32_16x16x32_bf16 v[88:91], v[204:207], v[236:239], v[88:91]
	v_mfma_f32_16x16x32_bf16 v[80:83], v[212:215], v[236:239], v[80:83]
	v_mfma_f32_16x16x32_bf16 v[72:75], v[204:207], v[244:247], v[72:75]
	v_mfma_f32_16x16x32_bf16 v[64:67], v[212:215], v[244:247], v[64:67]
	s_barrier
	s_setprio 0
	s_add_i32 s58, s58, s26
	v_lshl_add_u64 v[168:169], s[0:1], 0, v[144:145]
	s_mov_b32 m0, s58
	ds_read_b128 v[216:219], v197 offset:16384
	ds_read_b128 v[220:223], v197 offset:17408
	ds_read_b128 v[224:227], v197 offset:18432
	ds_read_b128 v[228:231], v197 offset:19456
	ds_read_b128 v[232:235], v197 offset:20480
	ds_read_b128 v[236:239], v197 offset:21504
	ds_read_b128 v[240:243], v197 offset:22528
	ds_read_b128 v[244:247], v197 offset:23552
	global_load_lds_dwordx4 v[168:169], off
	s_add_i32 m0, s58, 0x2000
	s_add_u32 s58, s0, 0x40000
	v_lshl_add_u64 v[172:173], s[0:1], 0, v[150:151]
	s_addc_u32 s59, s1, 0
	s_add_i32 s60, s60, s26
	global_load_lds_dwordx4 v[172:173], off
	v_lshl_add_u64 v[184:185], s[58:59], 0, v[144:145]
	s_mov_b32 m0, s60
	v_lshl_add_u64 v[186:187], s[6:7], 0, v[152:153]
	global_load_lds_dwordx4 v[184:185], off
	v_lshl_add_u64 v[184:185], s[58:59], 0, v[150:151]
	s_add_i32 m0, s60, 0x2000
	s_nop 0
	global_load_lds_dwordx4 v[184:185], off
	v_lshl_add_u64 v[184:185], s[6:7], 0, v[154:155]
	s_mov_b32 m0, s27
	s_nop 0
	global_load_lds_dwordx4 v[184:185], off
	s_mov_b32 m0, s28
	s_nop 0
	global_load_lds_dwordx4 v[186:187], off
	s_waitcnt vmcnt(16)
	s_cmp_lg_u32 vcc_lo, 0
	s_cbranch_scc1 .Lgu_relaxed1_p
	s_waitcnt vmcnt(8)
; #define PG8_STAGE(bufoff, gbase, voff) do { _Pragma("unroll") for (int _i = 0; _i < 2; ++_i) \
;         __builtin_amdgcn_global_load_lds((const unsigned*)((const char*)(gbase) + (voff)[_i]), (PG8_LAS unsigned*)(lds + (bufoff) + ldsw + _i * 8192), 16, 0, 0); } while (0)
; #define PG8_LDA(dst, b, h) do { _Pragma("unroll") for (int m = 0; m < 4; ++m) _Pragma("unroll") for (int k = 0; k < 2; ++k) dst[m][k] = *(const PG8_LAS bf16x8*)(lds + PG8_SA(b, h) + aoff + m * 2048 + k * 1024); } while (0)
; #define PG8_LDB(dst, b, h) do { _Pragma("unroll") for (int n = 0; n < 2; ++n) _Pragma("unroll") for (int k = 0; k < 2; ++k) dst[n][k] = *(const PG8_LAS bf16x8*)(lds + PG8_SB(b, h) + boff + n * 2048 + k * 1024); } while (0)
; #define PG8_MMA(ai, bj, At, Bt) do { __builtin_amdgcn_s_setprio(1); _Pragma("unroll") for (int m = 0; m < 4; ++m) _Pragma("unroll") for (int n = 0; n < 2; ++n) _Pragma("unroll") for (int k = 0; k < 2; ++k) \
;         acc[ai][bj][m][n] = __builtin_amdgcn_mfma_f32_16x16x32_bf16(Bt[n][k], At[m][k], acc[ai][bj][m][n], 0, 0, 0); __builtin_amdgcn_s_setprio(0); } while (0)
; #define PG8_WAIT_V(n) asm volatile("s_waitcnt vmcnt(" #n ")" ::: "memory")
; #define PG8_WAIT_L(n) asm volatile("s_waitcnt lgkmcnt(" #n ")" ::: "memory")
; #define PG8_BAR __builtin_amdgcn_s_barrier()
; #define PG8_SCHED __builtin_amdgcn_sched_barrier(0)
; template <class Epi, class Sched, bool ALIGN_EPI = false, bool SP2 = false>
; __device__ __forceinline__ void gemm_phase(PG8_LAS unsigned char* lds, const Gemm g, const Sched& S, const Epi& E) {
;     ...
;             PG8_WAIT_V(8); PG8_WAIT_L(0); PG8_BAR; PG8_MMA(0, 0, At, B0); PG8_MMA(0, 1, At, B1); PG8_BAR; PG8_SCHED;
;             PG8_LDA(At, 0, 1); PG8_STAGE(PG8_SB(0, 0), b2, voffB); PG8_STAGE(PG8_SB(0, 1), b2 + hstep, voffB); PG8_STAGE(PG8_SA(0, 0), a2, voffA);
;             PG8_WAIT_V(8); PG8_WAIT_L(0); PG8_BAR; PG8_MMA(1, 0, At, B0); PG8_MMA(1, 1, At, B1); PG8_BAR; PG8_SCHED;
;             PG8_LDB(B0, 1, 0); PG8_LDB(B1, 1, 1); PG8_SCHED; PG8_LDA(At, 1, 0); PG8_STAGE(PG8_SA(0, 1), a2 + hstep, voffA);
;             PG8_WAIT_V(8); PG8_WAIT_L(0); PG8_BAR; PG8_MMA(0, 0, At, B0); PG8_MMA(0, 1, At, B1); PG8_BAR; PG8_SCHED;
.Lgu_relaxed1_p:
	s_waitcnt lgkmcnt(0)
	.p2alignl 3, 3212836864
	s_setprio 1
	s_barrier
	v_mfma_f32_16x16x32_bf16 v[60:63], v[132:135], v[216:219], 0
	v_mfma_f32_16x16x32_bf16 v[52:55], v[140:143], v[216:219], 0
	v_mfma_f32_16x16x32_bf16 v[44:47], v[132:135], v[224:227], 0
	v_mfma_f32_16x16x32_bf16 v[36:39], v[140:143], v[224:227], 0
	v_mfma_f32_16x16x32_bf16 v[28:31], v[132:135], v[232:235], 0
	v_mfma_f32_16x16x32_bf16 v[20:23], v[140:143], v[232:235], 0
	v_mfma_f32_16x16x32_bf16 v[12:15], v[132:135], v[240:243], 0
	v_mfma_f32_16x16x32_bf16 v[4:7], v[140:143], v[240:243], 0
	v_mfma_f32_16x16x32_bf16 v[60:63], v[136:139], v[220:223], v[60:63]
	v_mfma_f32_16x16x32_bf16 v[52:55], v[180:183], v[220:223], v[52:55]
	v_mfma_f32_16x16x32_bf16 v[44:47], v[136:139], v[228:231], v[44:47]
	v_mfma_f32_16x16x32_bf16 v[36:39], v[180:183], v[228:231], v[36:39]
	v_mfma_f32_16x16x32_bf16 v[28:31], v[136:139], v[236:239], v[28:31]
	v_mfma_f32_16x16x32_bf16 v[20:23], v[180:183], v[236:239], v[20:23]
	v_mfma_f32_16x16x32_bf16 v[12:15], v[136:139], v[244:247], v[12:15]
	v_mfma_f32_16x16x32_bf16 v[4:7], v[180:183], v[244:247], v[4:7]
	s_setprio 0
	s_setprio 1
	v_mfma_f32_16x16x32_bf16 v[56:59], v[200:203], v[216:219], 0
	v_mfma_f32_16x16x32_bf16 v[48:51], v[208:211], v[216:219], 0
	v_mfma_f32_16x16x32_bf16 v[40:43], v[200:203], v[224:227], 0
	v_mfma_f32_16x16x32_bf16 v[32:35], v[208:211], v[224:227], 0
	v_mfma_f32_16x16x32_bf16 v[24:27], v[200:203], v[232:235], 0
	v_mfma_f32_16x16x32_bf16 v[16:19], v[208:211], v[232:235], 0
	v_mfma_f32_16x16x32_bf16 v[8:11], v[200:203], v[240:243], 0
	v_mfma_f32_16x16x32_bf16 v[0:3], v[208:211], v[240:243], 0
	v_mfma_f32_16x16x32_bf16 v[56:59], v[204:207], v[220:223], v[56:59]
	v_mfma_f32_16x16x32_bf16 v[48:51], v[212:215], v[220:223], v[48:51]
	v_mfma_f32_16x16x32_bf16 v[40:43], v[204:207], v[228:231], v[40:43]
	v_mfma_f32_16x16x32_bf16 v[32:35], v[212:215], v[228:231], v[32:35]
	v_mfma_f32_16x16x32_bf16 v[24:27], v[204:207], v[236:239], v[24:27]
	v_mfma_f32_16x16x32_bf16 v[16:19], v[212:215], v[236:239], v[16:19]
	v_mfma_f32_16x16x32_bf16 v[8:11], v[204:207], v[244:247], v[8:11]
	v_mfma_f32_16x16x32_bf16 v[0:3], v[212:215], v[244:247], v[0:3]
	s_barrier
	s_setprio 0
	s_add_i32 s58, 0, 0x18000
	v_add_u32_e32 v162, s58, v165
	s_add_i32 s59, 0, 0x1c000
	ds_read_b128 v[132:135], v162
	ds_read_b128 v[136:139], v162 offset:1024
	ds_read_b128 v[140:143], v162 offset:2048
	ds_read_b128 v[180:183], v162 offset:3072
	v_add_u32_e32 v162, s59, v165
	ds_read_b128 v[200:203], v162
	ds_read_b128 v[204:207], v162 offset:1024
	ds_read_b128 v[208:211], v162 offset:2048
	ds_read_b128 v[212:215], v162 offset:3072
	s_add_u32 s6, s6, 0x40000
	s_addc_u32 s7, s7, 0
	s_mov_b32 m0, s29
	v_lshl_add_u64 v[188:189], s[6:7], 0, v[154:155]
	ds_read_b128 v[216:219], v197 offset:32768
	ds_read_b128 v[220:223], v197 offset:33792
	ds_read_b128 v[224:227], v197 offset:34816
	ds_read_b128 v[228:231], v197 offset:35840
	ds_read_b128 v[232:235], v197 offset:36864
	ds_read_b128 v[236:239], v197 offset:37888
	ds_read_b128 v[240:243], v197 offset:38912
	ds_read_b128 v[244:247], v197 offset:39936
	global_load_lds_dwordx4 v[188:189], off
	v_lshl_add_u64 v[188:189], s[6:7], 0, v[152:153]
	s_mov_b32 m0, s30
	s_nop 0
	global_load_lds_dwordx4 v[188:189], off
	s_waitcnt vmcnt(8)
	s_waitcnt lgkmcnt(0)
	.p2alignl 3, 3212836864
	s_setprio 1
	s_barrier
	v_mfma_f32_16x16x32_bf16 v[124:127], v[132:135], v[216:219], v[124:127]
	v_mfma_f32_16x16x32_bf16 v[116:119], v[140:143], v[216:219], v[116:119]
	v_mfma_f32_16x16x32_bf16 v[108:111], v[132:135], v[224:227], v[108:111]
	v_mfma_f32_16x16x32_bf16 v[100:103], v[140:143], v[224:227], v[100:103]
	v_mfma_f32_16x16x32_bf16 v[92:95], v[132:135], v[232:235], v[92:95]
	v_mfma_f32_16x16x32_bf16 v[84:87], v[140:143], v[232:235], v[84:87]
	v_mfma_f32_16x16x32_bf16 v[76:79], v[132:135], v[240:243], v[76:79]
	v_mfma_f32_16x16x32_bf16 v[68:71], v[140:143], v[240:243], v[68:71]
	v_mfma_f32_16x16x32_bf16 v[124:127], v[136:139], v[220:223], v[124:127]
	v_mfma_f32_16x16x32_bf16 v[116:119], v[180:183], v[220:223], v[116:119]
	v_mfma_f32_16x16x32_bf16 v[108:111], v[136:139], v[228:231], v[108:111]
	v_mfma_f32_16x16x32_bf16 v[100:103], v[180:183], v[228:231], v[100:103]
	v_mfma_f32_16x16x32_bf16 v[92:95], v[136:139], v[236:239], v[92:95]
	v_mfma_f32_16x16x32_bf16 v[84:87], v[180:183], v[236:239], v[84:87]
	v_mfma_f32_16x16x32_bf16 v[76:79], v[136:139], v[244:247], v[76:79]
	v_mfma_f32_16x16x32_bf16 v[68:71], v[180:183], v[244:247], v[68:71]
	s_setprio 0
	s_setprio 1
	v_mfma_f32_16x16x32_bf16 v[120:123], v[200:203], v[216:219], v[120:123]
	v_mfma_f32_16x16x32_bf16 v[112:115], v[208:211], v[216:219], v[112:115]
	v_mfma_f32_16x16x32_bf16 v[104:107], v[200:203], v[224:227], v[104:107]
	v_mfma_f32_16x16x32_bf16 v[96:99], v[208:211], v[224:227], v[96:99]
	v_mfma_f32_16x16x32_bf16 v[88:91], v[200:203], v[232:235], v[88:91]
	v_mfma_f32_16x16x32_bf16 v[80:83], v[208:211], v[232:235], v[80:83]
	v_mfma_f32_16x16x32_bf16 v[72:75], v[200:203], v[240:243], v[72:75]
	v_mfma_f32_16x16x32_bf16 v[64:67], v[208:211], v[240:243], v[64:67]
	v_mfma_f32_16x16x32_bf16 v[120:123], v[204:207], v[220:223], v[120:123]
	v_mfma_f32_16x16x32_bf16 v[112:115], v[212:215], v[220:223], v[112:115]
	v_mfma_f32_16x16x32_bf16 v[104:107], v[204:207], v[228:231], v[104:107]
	v_mfma_f32_16x16x32_bf16 v[96:99], v[212:215], v[228:231], v[96:99]
	v_mfma_f32_16x16x32_bf16 v[88:91], v[204:207], v[236:239], v[88:91]
	v_mfma_f32_16x16x32_bf16 v[80:83], v[212:215], v[236:239], v[80:83]
	v_mfma_f32_16x16x32_bf16 v[72:75], v[204:207], v[244:247], v[72:75]
	v_mfma_f32_16x16x32_bf16 v[64:67], v[212:215], v[244:247], v[64:67]
	s_barrier
; #define PG8_STAGE(bufoff, gbase, voff) do { _Pragma("unroll") for (int _i = 0; _i < 2; ++_i) \
;         __builtin_amdgcn_global_load_lds((const unsigned*)((const char*)(gbase) + (voff)[_i]), (PG8_LAS unsigned*)(lds + (bufoff) + ldsw + _i * 8192), 16, 0, 0); } while (0)
; #define PG8_LDA(dst, b, h) do { _Pragma("unroll") for (int m = 0; m < 4; ++m) _Pragma("unroll") for (int k = 0; k < 2; ++k) dst[m][k] = *(const PG8_LAS bf16x8*)(lds + PG8_SA(b, h) + aoff + m * 2048 + k * 1024); } while (0)
; #define PG8_MMA(ai, bj, At, Bt) do { __builtin_amdgcn_s_setprio(1); _Pragma("unroll") for (int m = 0; m < 4; ++m) _Pragma("unroll") for (int n = 0; n < 2; ++n) _Pragma("unroll") for (int k = 0; k < 2; ++k) \
;         acc[ai][bj][m][n] = __builtin_amdgcn_mfma_f32_16x16x32_bf16(Bt[n][k], At[m][k], acc[ai][bj][m][n], 0, 0, 0); __builtin_amdgcn_s_setprio(0); } while (0)
; #define PG8_WAIT_V(n) asm volatile("s_waitcnt vmcnt(" #n ")" ::: "memory")
; #define PG8_WAIT_L(n) asm volatile("s_waitcnt lgkmcnt(" #n ")" ::: "memory")
; #define PG8_BAR __builtin_amdgcn_s_barrier()
; #define PG8_SCHED __builtin_amdgcn_sched_barrier(0)
; template <class Epi, class Sched, bool ALIGN_EPI = false, bool SP2 = false>
; __device__ __forceinline__ void gemm_phase(PG8_LAS unsigned char* lds, const Gemm g, const Sched& S, const Epi& E) {
;     ...
;             PG8_WAIT_V(8); PG8_WAIT_L(0); PG8_BAR; PG8_MMA(0, 0, At, B0); PG8_MMA(0, 1, At, B1); PG8_BAR; PG8_SCHED;
;             PG8_LDA(At, 1, 1); PG8_STAGE(PG8_SB(1, 0), b3, voffB); PG8_STAGE(PG8_SB(1, 1), b3 + hstep, voffB); PG8_STAGE(PG8_SA(1, 0), a3, voffA);
;             PG8_WAIT_V(8); PG8_WAIT_L(0); PG8_BAR; PG8_MMA(1, 0, At, B0); PG8_MMA(1, 1, At, B1); PG8_BAR; PG8_SCHED;
	s_setprio 0
	s_add_i32 s6, s58, s26
	v_lshl_add_u64 v[168:169], v[168:169], 0, s[94:95]
	s_mov_b32 m0, s6
	ds_read_b128 v[216:219], v197 offset:49152
	ds_read_b128 v[220:223], v197 offset:50176
	ds_read_b128 v[224:227], v197 offset:51200
	ds_read_b128 v[228:231], v197 offset:52224
	ds_read_b128 v[232:235], v197 offset:53248
	ds_read_b128 v[236:239], v197 offset:54272
	ds_read_b128 v[240:243], v197 offset:55296
	ds_read_b128 v[244:247], v197 offset:56320
	global_load_lds_dwordx4 v[168:169], off
	s_add_i32 m0, s6, 0x2000
	s_add_u32 s0, s0, 0x40080
	v_lshl_add_u64 v[168:169], v[172:173], 0, s[94:95]
	s_addc_u32 s1, s1, 0
	s_add_i32 s6, s59, s26
	global_load_lds_dwordx4 v[168:169], off
	v_lshl_add_u64 v[168:169], s[0:1], 0, v[144:145]
	s_mov_b32 m0, s6
	s_nop 0
	global_load_lds_dwordx4 v[168:169], off
	v_lshl_add_u64 v[168:169], s[0:1], 0, v[150:151]
	s_add_i32 m0, s6, 0x2000
	s_nop 0
	global_load_lds_dwordx4 v[168:169], off
	v_lshl_add_u64 v[168:169], v[184:185], 0, s[94:95]
	s_mov_b32 m0, s31
	s_nop 0
	global_load_lds_dwordx4 v[168:169], off
	v_lshl_add_u64 v[168:169], v[186:187], 0, s[94:95]
	s_mov_b32 m0, s34
	s_nop 0
	global_load_lds_dwordx4 v[168:169], off
	s_waitcnt vmcnt(8)
	s_waitcnt lgkmcnt(0)
	.p2alignl 3, 3212836864
	s_setprio 1
	s_barrier
	v_mfma_f32_16x16x32_bf16 v[60:63], v[132:135], v[216:219], v[60:63]
	v_mfma_f32_16x16x32_bf16 v[52:55], v[140:143], v[216:219], v[52:55]
	v_mfma_f32_16x16x32_bf16 v[44:47], v[132:135], v[224:227], v[44:47]
	v_mfma_f32_16x16x32_bf16 v[36:39], v[140:143], v[224:227], v[36:39]
	v_mfma_f32_16x16x32_bf16 v[28:31], v[132:135], v[232:235], v[28:31]
	v_mfma_f32_16x16x32_bf16 v[20:23], v[140:143], v[232:235], v[20:23]
	v_mfma_f32_16x16x32_bf16 v[12:15], v[132:135], v[240:243], v[12:15]
	v_mfma_f32_16x16x32_bf16 v[4:7], v[140:143], v[240:243], v[4:7]
	v_mfma_f32_16x16x32_bf16 v[60:63], v[136:139], v[220:223], v[60:63]
	v_mfma_f32_16x16x32_bf16 v[52:55], v[180:183], v[220:223], v[52:55]
	v_mfma_f32_16x16x32_bf16 v[44:47], v[136:139], v[228:231], v[44:47]
	v_mfma_f32_16x16x32_bf16 v[36:39], v[180:183], v[228:231], v[36:39]
	v_mfma_f32_16x16x32_bf16 v[28:31], v[136:139], v[236:239], v[28:31]
	v_mfma_f32_16x16x32_bf16 v[20:23], v[180:183], v[236:239], v[20:23]
	v_mfma_f32_16x16x32_bf16 v[12:15], v[136:139], v[244:247], v[12:15]
	v_mfma_f32_16x16x32_bf16 v[4:7], v[180:183], v[244:247], v[4:7]
	s_setprio 0
	s_setprio 1
	v_mfma_f32_16x16x32_bf16 v[56:59], v[200:203], v[216:219], v[56:59]
	v_mfma_f32_16x16x32_bf16 v[48:51], v[208:211], v[216:219], v[48:51]
	v_mfma_f32_16x16x32_bf16 v[40:43], v[200:203], v[224:227], v[40:43]
	v_mfma_f32_16x16x32_bf16 v[32:35], v[208:211], v[224:227], v[32:35]
	v_mfma_f32_16x16x32_bf16 v[24:27], v[200:203], v[232:235], v[24:27]
	v_mfma_f32_16x16x32_bf16 v[16:19], v[208:211], v[232:235], v[16:19]
	v_mfma_f32_16x16x32_bf16 v[8:11], v[200:203], v[240:243], v[8:11]
	v_mfma_f32_16x16x32_bf16 v[0:3], v[208:211], v[240:243], v[0:3]
	v_mfma_f32_16x16x32_bf16 v[56:59], v[204:207], v[220:223], v[56:59]
	v_mfma_f32_16x16x32_bf16 v[48:51], v[212:215], v[220:223], v[48:51]
	v_mfma_f32_16x16x32_bf16 v[40:43], v[204:207], v[228:231], v[40:43]
	v_mfma_f32_16x16x32_bf16 v[32:35], v[212:215], v[228:231], v[32:35]
	v_mfma_f32_16x16x32_bf16 v[24:27], v[204:207], v[236:239], v[24:27]
	v_mfma_f32_16x16x32_bf16 v[16:19], v[212:215], v[236:239], v[16:19]
	v_mfma_f32_16x16x32_bf16 v[8:11], v[204:207], v[244:247], v[8:11]
	v_mfma_f32_16x16x32_bf16 v[0:3], v[212:215], v[244:247], v[0:3]
	s_barrier
	s_setprio 0
	s_add_i32 s57, s57, 2
	s_add_u32 s4, s4, 0x100
	s_addc_u32 s5, s5, 0
	s_add_u32 s55, s55, 0x100
	s_addc_u32 s56, s56, 0
	s_cmp_gt_u32 s57, 13
	s_branch .LBB0_1648
